# MLA step A: one softmax half-part per MFMA gap (12 QK + 4 PV gaps), K fragments d0=2/3 re-targeted, row-max chain in last 4 PV gaps
# speedup vs baseline: 1.0133x; 1.0037x over previous
.LBB0_295:
	v_lshl_add_u64 v[114:115], s[80:81], 0, v[224:225]
	global_load_dwordx4 v[178:181], v[114:115], off
	s_waitcnt lgkmcnt(3)
	v_mfma_f32_32x32x16_bf16 v[114:129], v[84:87], v[166:169], v[34:49]
	ds_read_b128 v[92:95], v254 offset:14336
	ds_read_b128 v[190:193], v254 offset:14848
	v_exp_f32_e32 v50, v50
	v_exp_f32_e32 v51, v51
	v_add_f32_e32 v236, v130, v50
	v_cvt_pk_bf16_f32 v84, v50, v51
	v_add_f32_e32 v237, v131, v51
	s_waitcnt lgkmcnt(4)
	v_mfma_f32_32x32x16_bf16 v[130:145], v[88:91], v[166:169], v[34:49]
	v_exp_f32_e32 v52, v52
	v_exp_f32_e32 v53, v53
	v_add_f32_e32 v236, v236, v52
	v_cvt_pk_bf16_f32 v85, v52, v53
	v_add_f32_e32 v237, v237, v53
	s_waitcnt lgkmcnt(1)
	v_mfma_f32_32x32x16_bf16 v[114:129], v[92:95], v[162:165], v[114:129]
	ds_read_b128 v[50:53], v254 offset:16384
	ds_read_b128 v[88:91], v254 offset:16896
	v_exp_f32_e32 v54, v54
	v_exp_f32_e32 v55, v55
	v_add_f32_e32 v236, v236, v54
	v_cvt_pk_bf16_f32 v86, v54, v55
	v_add_f32_e32 v237, v237, v55
	s_waitcnt lgkmcnt(2)
	v_mfma_f32_32x32x16_bf16 v[130:145], v[190:193], v[162:165], v[130:145]
	v_exp_f32_e32 v56, v56
	v_exp_f32_e32 v57, v57
	v_add_f32_e32 v236, v236, v56
	v_cvt_pk_bf16_f32 v87, v56, v57
	v_add_f32_e32 v237, v237, v57
	s_waitcnt lgkmcnt(1)
	v_mfma_f32_32x32x16_bf16 v[114:129], v[50:53], v[158:161], v[114:129]
	ds_read_b128 v[54:57], v254 offset:18432
	ds_read_b128 v[190:193], v254 offset:18944
	v_exp_f32_e32 v58, v58
	v_exp_f32_e32 v59, v59
	v_add_f32_e32 v236, v236, v58
	v_cvt_pk_bf16_f32 v58, v58, v59
	v_add_f32_e32 v237, v237, v59
	s_waitcnt lgkmcnt(2)
	v_mfma_f32_32x32x16_bf16 v[130:145], v[88:91], v[158:161], v[130:145]
	v_exp_f32_e32 v60, v60
	v_exp_f32_e32 v61, v61
	v_add_f32_e32 v236, v236, v60
	v_cvt_pk_bf16_f32 v59, v60, v61
	v_add_f32_e32 v237, v237, v61
	s_waitcnt lgkmcnt(1)
	v_mfma_f32_32x32x16_bf16 v[114:129], v[54:57], v[154:157], v[114:129]
	ds_read_b128 v[88:91], v254 offset:20480
	ds_read_b128 v[92:95], v254 offset:20992
	v_exp_f32_e32 v62, v62
	v_exp_f32_e32 v63, v63
	v_add_f32_e32 v236, v236, v62
	v_cvt_pk_bf16_f32 v60, v62, v63
	v_add_f32_e32 v237, v237, v63
	s_waitcnt lgkmcnt(2)
	v_mfma_f32_32x32x16_bf16 v[130:145], v[190:193], v[154:157], v[130:145]
	v_exp_f32_e32 v64, v64
	v_exp_f32_e32 v65, v65
	v_add_f32_e32 v236, v236, v64
	v_cvt_pk_bf16_f32 v61, v64, v65
	v_add_f32_e32 v237, v237, v65
	s_waitcnt lgkmcnt(1)
	v_mfma_f32_32x32x16_bf16 v[114:129], v[88:91], v[150:153], v[114:129]
	ds_read_b128 v[54:57], v254 offset:22528
	ds_read_b128 v[62:65], v254 offset:23040
	v_exp_f32_e32 v66, v66
	v_exp_f32_e32 v67, v67
	v_add_f32_e32 v236, v236, v66
	v_cvt_pk_bf16_f32 v50, v66, v67
	v_add_f32_e32 v237, v237, v67
	s_waitcnt lgkmcnt(2)
	v_mfma_f32_32x32x16_bf16 v[130:145], v[92:95], v[150:153], v[130:145]
	v_exp_f32_e32 v68, v68
	v_exp_f32_e32 v69, v69
	v_add_f32_e32 v236, v236, v68
	v_cvt_pk_bf16_f32 v51, v68, v69
	v_add_f32_e32 v237, v237, v69
	s_waitcnt lgkmcnt(1)
	v_mfma_f32_32x32x16_bf16 v[114:129], v[54:57], v[146:149], v[114:129]
	v_exp_f32_e32 v70, v70
	v_exp_f32_e32 v71, v71
	v_add_f32_e32 v236, v236, v70
	v_cvt_pk_bf16_f32 v52, v70, v71
	v_add_f32_e32 v237, v237, v71
	s_waitcnt lgkmcnt(0)
	v_mfma_f32_32x32x16_bf16 v[130:145], v[62:65], v[146:149], v[130:145]
	ds_read_b64_tr_b16 v[54:55], v243 offset:24576
	ds_read_b64_tr_b16 v[56:57], v243 offset:25088
	ds_read_b64_tr_b16 v[62:63], v243 offset:28672
	ds_read_b64_tr_b16 v[64:65], v243 offset:29184
	v_exp_f32_e32 v72, v72
	v_exp_f32_e32 v73, v73
	v_add_f32_e32 v236, v236, v72
	v_cvt_pk_bf16_f32 v53, v72, v73
	v_add_f32_e32 v237, v237, v73
	s_waitcnt lgkmcnt(2)
	v_mfma_f32_32x32x16_bf16 v[18:33], v[84:87], v[54:57], v[18:33]
	ds_read_b64_tr_b16 v[68:69], v243 offset:25600
	ds_read_b64_tr_b16 v[70:71], v243 offset:26112
	v_exp_f32_e32 v74, v74
	v_exp_f32_e32 v75, v75
	v_add_f32_e32 v236, v236, v74
	v_cvt_pk_bf16_f32 v74, v74, v75
	v_add_f32_e32 v237, v237, v75
	s_waitcnt lgkmcnt(2)
	v_mfma_f32_32x32x16_bf16 v[2:17], v[84:87], v[62:65], v[2:17]
	ds_read_b64_tr_b16 v[54:55], v243 offset:29696
	ds_read_b64_tr_b16 v[56:57], v243 offset:30208
	v_exp_f32_e32 v76, v76
	v_exp_f32_e32 v77, v77
	v_add_f32_e32 v236, v236, v76
	v_cvt_pk_bf16_f32 v75, v76, v77
	v_add_f32_e32 v237, v237, v77
	s_waitcnt lgkmcnt(2)
	v_mfma_f32_32x32x16_bf16 v[18:33], v[58:61], v[68:71], v[18:33]
	ds_read_b64_tr_b16 v[62:63], v243 offset:26624
	ds_read_b64_tr_b16 v[64:65], v243 offset:27136
	v_exp_f32_e32 v78, v78
	v_exp_f32_e32 v79, v79
	v_add_f32_e32 v236, v236, v78
	v_cvt_pk_bf16_f32 v76, v78, v79
	v_add_f32_e32 v237, v237, v79
	s_waitcnt lgkmcnt(2)
	v_mfma_f32_32x32x16_bf16 v[2:17], v[58:61], v[54:57], v[2:17]
	ds_read_b64_tr_b16 v[68:69], v243 offset:30720
	ds_read_b64_tr_b16 v[70:71], v243 offset:31232
	v_exp_f32_e32 v80, v80
	v_exp_f32_e32 v81, v81
	v_add_f32_e32 v66, v236, v80
	v_cvt_pk_bf16_f32 v77, v80, v81
	v_add_f32_e32 v67, v237, v81
	s_waitcnt lgkmcnt(2)
	v_mfma_f32_32x32x16_bf16 v[18:33], v[50:53], v[62:65], v[18:33]
	ds_read_b64_tr_b16 v[54:55], v243 offset:27648
	ds_read_b64_tr_b16 v[56:57], v243 offset:28160
	v_max_f32_e32 v72, v114, v114
	v_max_f32_e32 v72, 0xf149f2ca, v72
	v_max3_f32 v73, v130, s25, v131
	v_max3_f32 v72, v72, v115, v116
	v_max3_f32 v73, v73, v132, v133
	s_waitcnt lgkmcnt(2)
	v_mfma_f32_32x32x16_bf16 v[2:17], v[50:53], v[68:71], v[2:17]
	ds_read_b64_tr_b16 v[58:59], v243 offset:31744
	ds_read_b64_tr_b16 v[60:61], v243 offset:32256
	v_max3_f32 v72, v72, v117, v118
	v_max3_f32 v73, v73, v134, v135
	v_max3_f32 v72, v72, v119, v120
	v_max3_f32 v73, v73, v136, v137
	s_waitcnt lgkmcnt(2)
	v_mfma_f32_32x32x16_bf16 v[18:33], v[74:77], v[54:57], v[18:33]
	v_max3_f32 v72, v72, v121, v122
	v_max3_f32 v73, v73, v138, v139
	v_max3_f32 v72, v72, v123, v124
	v_max3_f32 v73, v73, v140, v141
	s_waitcnt lgkmcnt(0)
	v_mfma_f32_32x32x16_bf16 v[2:17], v[74:77], v[58:61], v[2:17]
	v_max3_f32 v72, v72, v125, v126
	v_max3_f32 v73, v73, v142, v143
	v_max3_f32 v72, v72, v127, v128
	v_max3_f32 v73, v73, v144, v145
	v_max3_f32 v50, v72, v129, v73
	v_cmp_lt_f32_e32 vcc, s16, v50
	s_barrier
	s_cbranch_vccz .LBB0_299
	ds_bpermute_b32 v34, v251, v50
	s_waitcnt lgkmcnt(0)
	v_max3_f32 v35, v50, v34, 0
	v_exp_f32_e64 v34, -v35
	s_and_saveexec_b64 s[12:13], s[6:7]
	ds_write_b32 v209, v34 offset:57344
	s_or_b64 exec, exec, s[12:13]
	ds_read_b128 v[36:39], v207 offset:57408
	ds_read_b128 v[40:43], v207 offset:57440
	ds_read_b128 v[44:47], v207 offset:57344
	ds_read_b128 v[48:51], v207 offset:57376
	v_add_f32_e32 v229, v229, v35
	v_xor_b32_e32 v82, 0x80000000, v229
	v_mov_b32_e32 v83, v82
	v_sub_f32_e32 v129, v129, v35
	v_sub_f32_e32 v128, v128, v35
	v_sub_f32_e32 v127, v127, v35
	v_sub_f32_e32 v126, v126, v35
	v_sub_f32_e32 v125, v125, v35
	v_sub_f32_e32 v124, v124, v35
	v_sub_f32_e32 v123, v123, v35
	v_sub_f32_e32 v122, v122, v35
	v_sub_f32_e32 v121, v121, v35
	v_sub_f32_e32 v120, v120, v35
	v_sub_f32_e32 v119, v119, v35
	v_sub_f32_e32 v118, v118, v35
	v_sub_f32_e32 v117, v117, v35
	v_sub_f32_e32 v116, v116, v35
	v_sub_f32_e32 v115, v115, v35
	v_sub_f32_e32 v114, v114, v35
	v_sub_f32_e32 v145, v145, v35
	v_sub_f32_e32 v144, v144, v35
	v_sub_f32_e32 v143, v143, v35
	v_sub_f32_e32 v142, v142, v35
	v_sub_f32_e32 v141, v141, v35
	v_sub_f32_e32 v140, v140, v35
	v_sub_f32_e32 v139, v139, v35
	v_sub_f32_e32 v138, v138, v35
	v_sub_f32_e32 v137, v137, v35
	v_sub_f32_e32 v136, v136, v35
	v_sub_f32_e32 v135, v135, v35
	v_sub_f32_e32 v134, v134, v35
	v_sub_f32_e32 v133, v133, v35
	v_sub_f32_e32 v132, v132, v35
	v_sub_f32_e32 v131, v131, v35
	v_sub_f32_e32 v130, v130, v35
	v_pk_mul_f32 v[66:67], v[66:67], v[34:35] op_sel_hi:[1,0]
	s_waitcnt lgkmcnt(2)
	v_pk_mul_f32 v[32:33], v[32:33], v[42:43]
	v_pk_mul_f32 v[28:29], v[28:29], v[38:39]
	s_waitcnt lgkmcnt(1)
	v_pk_mul_f32 v[20:21], v[20:21], v[46:47]
	v_pk_mul_f32 v[30:31], v[30:31], v[40:41]
	v_pk_mul_f32 v[26:27], v[26:27], v[36:37]
	s_waitcnt lgkmcnt(0)
	v_pk_mul_f32 v[22:23], v[22:23], v[48:49]
	v_pk_mul_f32 v[18:19], v[18:19], v[44:45]
	v_pk_mul_f32 v[16:17], v[16:17], v[42:43]
	v_pk_mul_f32 v[12:13], v[12:13], v[38:39]
	v_pk_mul_f32 v[4:5], v[4:5], v[46:47]
	v_pk_mul_f32 v[14:15], v[14:15], v[40:41]
	v_pk_mul_f32 v[10:11], v[10:11], v[36:37]
	v_pk_mul_f32 v[6:7], v[6:7], v[48:49]
	v_pk_mul_f32 v[2:3], v[2:3], v[44:45]
	v_mov_b32_e32 v84, v82
	v_mov_b32_e32 v85, v82
	v_mov_b32_e32 v86, v82
	v_mov_b32_e32 v87, v82
	v_mov_b32_e32 v88, v82
	v_mov_b32_e32 v89, v82
	v_mov_b32_e32 v90, v82
	v_mov_b32_e32 v91, v82
	v_mov_b32_e32 v92, v82
	v_mov_b32_e32 v93, v82
	v_mov_b32_e32 v94, v82
	v_mov_b32_e32 v95, v82
	v_mov_b32_e32 v96, v82
	v_mov_b32_e32 v97, v82
	v_mov_b64_e32 v[34:35], v[82:83]
	v_pk_mul_f32 v[24:25], v[24:25], v[50:51]
	v_pk_mul_f32 v[8:9], v[8:9], v[50:51]
	v_mov_b32_e32 v112, v82
	v_mov_b32_e32 v111, v82
	v_mov_b32_e32 v110, v82
	v_mov_b32_e32 v109, v82
	v_mov_b32_e32 v108, v82
	v_mov_b32_e32 v107, v82
	v_mov_b32_e32 v106, v82
	v_mov_b32_e32 v105, v82
	v_mov_b32_e32 v104, v82
	v_mov_b32_e32 v103, v82
	v_mov_b32_e32 v102, v82
	v_mov_b32_e32 v101, v82
	v_mov_b32_e32 v100, v82
	v_mov_b32_e32 v99, v82
	v_mov_b32_e32 v98, v82
	v_mov_b64_e32 v[36:37], v[84:85]
	v_mov_b64_e32 v[38:39], v[86:87]
	v_mov_b64_e32 v[40:41], v[88:89]
	v_mov_b64_e32 v[42:43], v[90:91]
	v_mov_b64_e32 v[44:45], v[92:93]
	v_mov_b64_e32 v[46:47], v[94:95]
	v_mov_b64_e32 v[48:49], v[96:97]
